# code placement: every GEMM K-loop head padded back to its baseline offset mod 64
# speedup vs baseline: 1.0027x; 1.0027x over previous
.LBB0_332:
	s_ashr_i32 s49, s48, 31
	s_lshl_b64 s[18:19], s[48:49], 9
	v_readlane_b32 s33, v253, 24
	s_add_u32 s50, s33, s18
	v_readlane_b32 s18, v253, 25
	s_addc_u32 s51, s18, s19
	s_and_b64 s[18:19], s[42:43], exec
	s_cselect_b32 s18, s51, s57
	s_cselect_b32 s19, s50, s56
	s_ashr_i32 s45, s44, 31
	s_lshl_b64 s[52:53], s[44:45], 17
	v_readlane_b32 s58, v253, 20
	v_readlane_b32 s59, v253, 21
	s_add_u32 s52, s58, s52
	s_addc_u32 s53, s59, s53
	s_and_b64 s[58:59], s[42:43], exec
	v_mov_b32_e32 v2, 0
	s_cselect_b32 s33, s53, s55
	s_cselect_b32 s45, s52, s54
	s_mov_b32 s49, 0
	s_mov_b64 s[58:59], -1
	s_mov_b64 s[60:61], 0
	v_mov_b32_e32 v3, v2
	v_mov_b32_e32 v4, v2
	v_mov_b32_e32 v5, v2
	v_mov_b32_e32 v6, v2
	v_mov_b32_e32 v7, v2
	v_mov_b32_e32 v8, v2
	v_mov_b32_e32 v9, v2
	v_mov_b32_e32 v10, v2
	v_mov_b32_e32 v11, v2
	v_mov_b32_e32 v12, v2
	v_mov_b32_e32 v13, v2
	v_mov_b32_e32 v14, v2
	v_mov_b32_e32 v15, v2
	v_mov_b32_e32 v16, v2
	v_mov_b32_e32 v17, v2
	v_mov_b32_e32 v26, v2
	v_mov_b32_e32 v27, v2
	v_mov_b32_e32 v28, v2
	v_mov_b32_e32 v29, v2
	v_mov_b32_e32 v30, v2
	v_mov_b32_e32 v31, v2
	v_mov_b32_e32 v32, v2
	v_mov_b32_e32 v33, v2
	v_mov_b32_e32 v42, v2
	v_mov_b32_e32 v43, v2
	v_mov_b32_e32 v44, v2
	v_mov_b32_e32 v45, v2
	v_mov_b32_e32 v46, v2
	v_mov_b32_e32 v47, v2
	v_mov_b32_e32 v48, v2
	v_mov_b32_e32 v49, v2
	v_mov_b32_e32 v18, v2
	v_mov_b32_e32 v19, v2
	v_mov_b32_e32 v20, v2
	v_mov_b32_e32 v21, v2
	v_mov_b32_e32 v22, v2
	v_mov_b32_e32 v23, v2
	v_mov_b32_e32 v24, v2
	v_mov_b32_e32 v25, v2
	v_mov_b32_e32 v34, v2
	v_mov_b32_e32 v35, v2
	v_mov_b32_e32 v36, v2
	v_mov_b32_e32 v37, v2
	v_mov_b32_e32 v38, v2
	v_mov_b32_e32 v39, v2
	v_mov_b32_e32 v40, v2
	v_mov_b32_e32 v41, v2
	v_mov_b32_e32 v50, v2
	v_mov_b32_e32 v51, v2
	v_mov_b32_e32 v52, v2
	v_mov_b32_e32 v53, v2
	v_mov_b32_e32 v54, v2
	v_mov_b32_e32 v55, v2
	v_mov_b32_e32 v56, v2
	v_mov_b32_e32 v57, v2
	v_mov_b32_e32 v58, v2
	v_mov_b32_e32 v59, v2
	v_mov_b32_e32 v60, v2
	v_mov_b32_e32 v61, v2
	v_mov_b32_e32 v62, v2
	v_mov_b32_e32 v63, v2
	v_mov_b32_e32 v64, v2
	v_mov_b32_e32 v65, v2
	v_mov_b32_e32 v66, v2
	v_mov_b32_e32 v67, v2
	v_mov_b32_e32 v68, v2
	v_mov_b32_e32 v69, v2
	v_mov_b32_e32 v70, v2
	v_mov_b32_e32 v71, v2
	v_mov_b32_e32 v72, v2
	v_mov_b32_e32 v73, v2
	v_mov_b32_e32 v74, v2
	v_mov_b32_e32 v75, v2
	v_mov_b32_e32 v76, v2
	v_mov_b32_e32 v77, v2
	v_mov_b32_e32 v78, v2
	v_mov_b32_e32 v79, v2
	v_mov_b32_e32 v80, v2
	v_mov_b32_e32 v81, v2
	v_mov_b32_e32 v90, v2
	v_mov_b32_e32 v91, v2
	v_mov_b32_e32 v92, v2
	v_mov_b32_e32 v93, v2
	v_mov_b32_e32 v94, v2
	v_mov_b32_e32 v95, v2
	v_mov_b32_e32 v96, v2
	v_mov_b32_e32 v97, v2
	v_mov_b32_e32 v108, v2
	v_mov_b32_e32 v109, v2
	v_mov_b32_e32 v110, v2
	v_mov_b32_e32 v111, v2
	v_mov_b32_e32 v112, v2
	v_mov_b32_e32 v113, v2
	v_mov_b32_e32 v114, v2
	v_mov_b32_e32 v115, v2
	v_mov_b32_e32 v82, v2
	v_mov_b32_e32 v83, v2
	v_mov_b32_e32 v84, v2
	v_mov_b32_e32 v85, v2
	v_mov_b32_e32 v86, v2
	v_mov_b32_e32 v87, v2
	v_mov_b32_e32 v88, v2
	v_mov_b32_e32 v89, v2
	v_mov_b32_e32 v100, v2
	v_mov_b32_e32 v101, v2
	v_mov_b32_e32 v102, v2
	v_mov_b32_e32 v103, v2
	v_mov_b32_e32 v104, v2
	v_mov_b32_e32 v105, v2
	v_mov_b32_e32 v106, v2
	v_mov_b32_e32 v107, v2
	v_mov_b32_e32 v116, v2
	v_mov_b32_e32 v117, v2
	v_mov_b32_e32 v118, v2
	v_mov_b32_e32 v119, v2
	v_mov_b32_e32 v120, v2
	v_mov_b32_e32 v121, v2
	v_mov_b32_e32 v122, v2
	v_mov_b32_e32 v123, v2
	v_mov_b32_e32 v124, v2
	v_mov_b32_e32 v125, v2
	v_mov_b32_e32 v126, v2
	v_mov_b32_e32 v127, v2
	v_mov_b32_e32 v128, v2
	v_mov_b32_e32 v129, v2
	v_mov_b32_e32 v130, v2
	v_mov_b32_e32 v131, v2
	s_nop 0
	s_nop 0
	s_nop 0
	s_nop 0
	s_nop 0
	s_nop 0
	s_nop 0
	s_nop 0
	s_nop 0
	s_nop 0
	s_nop 0
	s_nop 0
	s_nop 0
	s_nop 0
	s_nop 0

.LBB0_646:
	s_ashr_i32 s49, s48, 31
	s_lshl_b64 s[52:53], s[48:49], 12
	s_add_u32 s49, s92, s52
	s_addc_u32 s53, s93, s53
	s_lshl_b32 s52, s59, 1
	s_ashr_i32 s63, s52, 31
	s_add_u32 s52, s49, s52
	s_addc_u32 s53, s53, s63
	s_and_b64 s[54:55], s[54:55], exec
	s_cselect_b32 s49, s53, s41
	s_cselect_b32 s63, s52, s40
	s_add_i32 s65, s62, -2
	s_add_u32 s40, s40, 0x80080
	s_addc_u32 s41, s41, 0
	s_add_u32 s66, s42, 0x100
	v_mov_b32_e32 v2, 0
	s_addc_u32 s67, s43, 0
	s_mov_b32 s42, 0
	v_mov_b32_e32 v3, v2
	v_mov_b32_e32 v4, v2
	v_mov_b32_e32 v5, v2
	v_mov_b32_e32 v6, v2
	v_mov_b32_e32 v7, v2
	v_mov_b32_e32 v8, v2
	v_mov_b32_e32 v9, v2
	v_mov_b32_e32 v18, v2
	v_mov_b32_e32 v19, v2
	v_mov_b32_e32 v20, v2
	v_mov_b32_e32 v21, v2
	v_mov_b32_e32 v22, v2
	v_mov_b32_e32 v23, v2
	v_mov_b32_e32 v24, v2
	v_mov_b32_e32 v25, v2
	v_mov_b32_e32 v34, v2
	v_mov_b32_e32 v35, v2
	v_mov_b32_e32 v36, v2
	v_mov_b32_e32 v37, v2
	v_mov_b32_e32 v38, v2
	v_mov_b32_e32 v39, v2
	v_mov_b32_e32 v40, v2
	v_mov_b32_e32 v41, v2
	v_mov_b32_e32 v50, v2
	v_mov_b32_e32 v51, v2
	v_mov_b32_e32 v52, v2
	v_mov_b32_e32 v53, v2
	v_mov_b32_e32 v54, v2
	v_mov_b32_e32 v55, v2
	v_mov_b32_e32 v56, v2
	v_mov_b32_e32 v57, v2
	v_mov_b32_e32 v10, v2
	v_mov_b32_e32 v11, v2
	v_mov_b32_e32 v12, v2
	v_mov_b32_e32 v13, v2
	v_mov_b32_e32 v14, v2
	v_mov_b32_e32 v15, v2
	v_mov_b32_e32 v16, v2
	v_mov_b32_e32 v17, v2
	v_mov_b32_e32 v26, v2
	v_mov_b32_e32 v27, v2
	v_mov_b32_e32 v28, v2
	v_mov_b32_e32 v29, v2
	v_mov_b32_e32 v30, v2
	v_mov_b32_e32 v31, v2
	v_mov_b32_e32 v32, v2
	v_mov_b32_e32 v33, v2
	v_mov_b32_e32 v42, v2
	v_mov_b32_e32 v43, v2
	v_mov_b32_e32 v44, v2
	v_mov_b32_e32 v45, v2
	v_mov_b32_e32 v46, v2
	v_mov_b32_e32 v47, v2
	v_mov_b32_e32 v48, v2
	v_mov_b32_e32 v49, v2
	v_mov_b32_e32 v58, v2
	v_mov_b32_e32 v59, v2
	v_mov_b32_e32 v60, v2
	v_mov_b32_e32 v61, v2
	v_mov_b32_e32 v62, v2
	v_mov_b32_e32 v63, v2
	v_mov_b32_e32 v64, v2
	v_mov_b32_e32 v65, v2
	v_mov_b32_e32 v66, v2
	v_mov_b32_e32 v67, v2
	v_mov_b32_e32 v68, v2
	v_mov_b32_e32 v69, v2
	v_mov_b32_e32 v70, v2
	v_mov_b32_e32 v71, v2
	v_mov_b32_e32 v72, v2
	v_mov_b32_e32 v73, v2
	v_mov_b32_e32 v82, v2
	v_mov_b32_e32 v83, v2
	v_mov_b32_e32 v84, v2
	v_mov_b32_e32 v85, v2
	v_mov_b32_e32 v86, v2
	v_mov_b32_e32 v87, v2
	v_mov_b32_e32 v88, v2
	v_mov_b32_e32 v89, v2
	v_mov_b32_e32 v100, v2
	v_mov_b32_e32 v101, v2
	v_mov_b32_e32 v102, v2
	v_mov_b32_e32 v103, v2
	v_mov_b32_e32 v104, v2
	v_mov_b32_e32 v105, v2
	v_mov_b32_e32 v106, v2
	v_mov_b32_e32 v107, v2
	v_mov_b32_e32 v116, v2
	v_mov_b32_e32 v117, v2
	v_mov_b32_e32 v118, v2
	v_mov_b32_e32 v119, v2
	v_mov_b32_e32 v120, v2
	v_mov_b32_e32 v121, v2
	v_mov_b32_e32 v122, v2
	v_mov_b32_e32 v123, v2
	v_mov_b32_e32 v74, v2
	v_mov_b32_e32 v75, v2
	v_mov_b32_e32 v76, v2
	v_mov_b32_e32 v77, v2
	v_mov_b32_e32 v78, v2
	v_mov_b32_e32 v79, v2
	v_mov_b32_e32 v80, v2
	v_mov_b32_e32 v81, v2
	v_mov_b32_e32 v90, v2
	v_mov_b32_e32 v91, v2
	v_mov_b32_e32 v92, v2
	v_mov_b32_e32 v93, v2
	v_mov_b32_e32 v94, v2
	v_mov_b32_e32 v95, v2
	v_mov_b32_e32 v96, v2
	v_mov_b32_e32 v97, v2
	v_mov_b32_e32 v108, v2
	v_mov_b32_e32 v109, v2
	v_mov_b32_e32 v110, v2
	v_mov_b32_e32 v111, v2
	v_mov_b32_e32 v112, v2
	v_mov_b32_e32 v113, v2
	v_mov_b32_e32 v114, v2
	v_mov_b32_e32 v115, v2
	v_mov_b32_e32 v124, v2
	v_mov_b32_e32 v125, v2
	v_mov_b32_e32 v126, v2
	v_mov_b32_e32 v127, v2
	v_mov_b32_e32 v128, v2
	v_mov_b32_e32 v129, v2
	v_mov_b32_e32 v130, v2
	v_mov_b32_e32 v131, v2
	s_nop 0
	s_nop 0
	s_nop 0

.LBB0_892:
	s_ashr_i32 s39, s38, 31
	s_lshl_b64 s[42:43], s[38:39], 10
	v_readlane_b32 s19, v253, 43
	s_add_u32 s42, s19, s42
	v_readlane_b32 s19, v253, 44
	s_addc_u32 s43, s19, s43
	s_and_b64 s[44:45], s[40:41], exec
	s_cselect_b32 s19, s43, s49
	s_cselect_b32 s33, s42, s48
	s_ashr_i32 s37, s36, 31
	s_lshl_b64 s[44:45], s[36:37], 18
	v_readlane_b32 s37, v253, 39
	s_add_u32 s44, s37, s44
	v_readlane_b32 s37, v253, 40
	s_addc_u32 s45, s37, s45
	s_and_b64 s[52:53], s[40:41], exec
	s_cselect_b32 s37, s45, s51
	s_cselect_b32 s39, s44, s50
	s_add_u32 s48, s48, 0x20080
	s_addc_u32 s49, s49, 0
	s_add_u32 s54, s50, 0x100
	v_mov_b32_e32 v2, 0
	s_addc_u32 s55, s51, 0
	s_mov_b32 s56, -2
	v_mov_b32_e32 v3, v2
	v_mov_b32_e32 v4, v2
	v_mov_b32_e32 v5, v2
	v_mov_b32_e32 v6, v2
	v_mov_b32_e32 v7, v2
	v_mov_b32_e32 v8, v2
	v_mov_b32_e32 v9, v2
	v_mov_b32_e32 v18, v2
	v_mov_b32_e32 v19, v2
	v_mov_b32_e32 v20, v2
	v_mov_b32_e32 v21, v2
	v_mov_b32_e32 v22, v2
	v_mov_b32_e32 v23, v2
	v_mov_b32_e32 v24, v2
	v_mov_b32_e32 v25, v2
	v_mov_b32_e32 v34, v2
	v_mov_b32_e32 v35, v2
	v_mov_b32_e32 v36, v2
	v_mov_b32_e32 v37, v2
	v_mov_b32_e32 v38, v2
	v_mov_b32_e32 v39, v2
	v_mov_b32_e32 v40, v2
	v_mov_b32_e32 v41, v2
	v_mov_b32_e32 v50, v2
	v_mov_b32_e32 v51, v2
	v_mov_b32_e32 v52, v2
	v_mov_b32_e32 v53, v2
	v_mov_b32_e32 v54, v2
	v_mov_b32_e32 v55, v2
	v_mov_b32_e32 v56, v2
	v_mov_b32_e32 v57, v2
	v_mov_b32_e32 v10, v2
	v_mov_b32_e32 v11, v2
	v_mov_b32_e32 v12, v2
	v_mov_b32_e32 v13, v2
	v_mov_b32_e32 v14, v2
	v_mov_b32_e32 v15, v2
	v_mov_b32_e32 v16, v2
	v_mov_b32_e32 v17, v2
	v_mov_b32_e32 v26, v2
	v_mov_b32_e32 v27, v2
	v_mov_b32_e32 v28, v2
	v_mov_b32_e32 v29, v2
	v_mov_b32_e32 v30, v2
	v_mov_b32_e32 v31, v2
	v_mov_b32_e32 v32, v2
	v_mov_b32_e32 v33, v2
	v_mov_b32_e32 v42, v2
	v_mov_b32_e32 v43, v2
	v_mov_b32_e32 v44, v2
	v_mov_b32_e32 v45, v2
	v_mov_b32_e32 v46, v2
	v_mov_b32_e32 v47, v2
	v_mov_b32_e32 v48, v2
	v_mov_b32_e32 v49, v2
	v_mov_b32_e32 v58, v2
	v_mov_b32_e32 v59, v2
	v_mov_b32_e32 v60, v2
	v_mov_b32_e32 v61, v2
	v_mov_b32_e32 v62, v2
	v_mov_b32_e32 v63, v2
	v_mov_b32_e32 v64, v2
	v_mov_b32_e32 v65, v2
	v_mov_b32_e32 v66, v2
	v_mov_b32_e32 v67, v2
	v_mov_b32_e32 v68, v2
	v_mov_b32_e32 v69, v2
	v_mov_b32_e32 v70, v2
	v_mov_b32_e32 v71, v2
	v_mov_b32_e32 v72, v2
	v_mov_b32_e32 v73, v2
	v_mov_b32_e32 v82, v2
	v_mov_b32_e32 v83, v2
	v_mov_b32_e32 v84, v2
	v_mov_b32_e32 v85, v2
	v_mov_b32_e32 v86, v2
	v_mov_b32_e32 v87, v2
	v_mov_b32_e32 v88, v2
	v_mov_b32_e32 v89, v2
	v_mov_b32_e32 v100, v2
	v_mov_b32_e32 v101, v2
	v_mov_b32_e32 v102, v2
	v_mov_b32_e32 v103, v2
	v_mov_b32_e32 v104, v2
	v_mov_b32_e32 v105, v2
	v_mov_b32_e32 v106, v2
	v_mov_b32_e32 v107, v2
	v_mov_b32_e32 v116, v2
	v_mov_b32_e32 v117, v2
	v_mov_b32_e32 v118, v2
	v_mov_b32_e32 v119, v2
	v_mov_b32_e32 v120, v2
	v_mov_b32_e32 v121, v2
	v_mov_b32_e32 v122, v2
	v_mov_b32_e32 v123, v2
	v_mov_b32_e32 v74, v2
	v_mov_b32_e32 v75, v2
	v_mov_b32_e32 v76, v2
	v_mov_b32_e32 v77, v2
	v_mov_b32_e32 v78, v2
	v_mov_b32_e32 v79, v2
	v_mov_b32_e32 v80, v2
	v_mov_b32_e32 v81, v2
	v_mov_b32_e32 v90, v2
	v_mov_b32_e32 v91, v2
	v_mov_b32_e32 v92, v2
	v_mov_b32_e32 v93, v2
	v_mov_b32_e32 v94, v2
	v_mov_b32_e32 v95, v2
	v_mov_b32_e32 v96, v2
	v_mov_b32_e32 v97, v2
	v_mov_b32_e32 v108, v2
	v_mov_b32_e32 v109, v2
	v_mov_b32_e32 v110, v2
	v_mov_b32_e32 v111, v2
	v_mov_b32_e32 v112, v2
	v_mov_b32_e32 v113, v2
	v_mov_b32_e32 v114, v2
	v_mov_b32_e32 v115, v2
	v_mov_b32_e32 v124, v2
	v_mov_b32_e32 v125, v2
	v_mov_b32_e32 v126, v2
	v_mov_b32_e32 v127, v2
	v_mov_b32_e32 v128, v2
	v_mov_b32_e32 v129, v2
	v_mov_b32_e32 v130, v2
	v_mov_b32_e32 v131, v2
	s_nop 0
	s_nop 0
	s_nop 0
	s_nop 0
	s_nop 0
	s_nop 0
	s_nop 0
	s_nop 0
	s_nop 0
	s_nop 0
	s_nop 0

.LBB0_1327:
	s_ashr_i32 s67, s66, 31
	s_lshl_b64 s[22:23], s[66:67], 11
	s_add_u32 s90, s96, s22
	s_mov_b32 s71, s91
	s_addc_u32 s91, s97, s23
	s_and_b64 s[22:23], s[38:39], exec
	s_cselect_b32 s1, s91, s43
	s_cselect_b32 s41, s90, s42
	s_ashr_i32 s65, s64, 31
	s_lshl_b64 s[22:23], s[64:65], 19
	s_add_u32 s22, s19, s22
	s_addc_u32 s23, s89, s23
	s_and_b64 s[46:47], s[38:39], exec
	s_cselect_b32 s48, s23, s45
	s_cselect_b32 s49, s22, s44
	s_add_u32 s42, s42, 0x40080
	s_addc_u32 s43, s43, 0
	s_add_u32 s50, s44, 0x100
	v_mov_b32_e32 v2, 0
	s_addc_u32 s51, s45, 0
	s_mov_b32 s52, -2
	v_mov_b32_e32 v3, v2
	v_mov_b32_e32 v4, v2
	v_mov_b32_e32 v5, v2
	v_mov_b32_e32 v6, v2
	v_mov_b32_e32 v7, v2
	v_mov_b32_e32 v8, v2
	v_mov_b32_e32 v9, v2
	v_mov_b32_e32 v18, v2
	v_mov_b32_e32 v19, v2
	v_mov_b32_e32 v20, v2
	v_mov_b32_e32 v21, v2
	v_mov_b32_e32 v22, v2
	v_mov_b32_e32 v23, v2
	v_mov_b32_e32 v24, v2
	v_mov_b32_e32 v25, v2
	v_mov_b32_e32 v34, v2
	v_mov_b32_e32 v35, v2
	v_mov_b32_e32 v36, v2
	v_mov_b32_e32 v37, v2
	v_mov_b32_e32 v38, v2
	v_mov_b32_e32 v39, v2
	v_mov_b32_e32 v40, v2
	v_mov_b32_e32 v41, v2
	v_mov_b32_e32 v50, v2
	v_mov_b32_e32 v51, v2
	v_mov_b32_e32 v52, v2
	v_mov_b32_e32 v53, v2
	v_mov_b32_e32 v54, v2
	v_mov_b32_e32 v55, v2
	v_mov_b32_e32 v56, v2
	v_mov_b32_e32 v57, v2
	v_mov_b32_e32 v10, v2
	v_mov_b32_e32 v11, v2
	v_mov_b32_e32 v12, v2
	v_mov_b32_e32 v13, v2
	v_mov_b32_e32 v14, v2
	v_mov_b32_e32 v15, v2
	v_mov_b32_e32 v16, v2
	v_mov_b32_e32 v17, v2
	v_mov_b32_e32 v26, v2
	v_mov_b32_e32 v27, v2
	v_mov_b32_e32 v28, v2
	v_mov_b32_e32 v29, v2
	v_mov_b32_e32 v30, v2
	v_mov_b32_e32 v31, v2
	v_mov_b32_e32 v32, v2
	v_mov_b32_e32 v33, v2
	v_mov_b32_e32 v42, v2
	v_mov_b32_e32 v43, v2
	v_mov_b32_e32 v44, v2
	v_mov_b32_e32 v45, v2
	v_mov_b32_e32 v46, v2
	v_mov_b32_e32 v47, v2
	v_mov_b32_e32 v48, v2
	v_mov_b32_e32 v49, v2
	v_mov_b32_e32 v58, v2
	v_mov_b32_e32 v59, v2
	v_mov_b32_e32 v60, v2
	v_mov_b32_e32 v61, v2
	v_mov_b32_e32 v62, v2
	v_mov_b32_e32 v63, v2
	v_mov_b32_e32 v64, v2
	v_mov_b32_e32 v65, v2
	v_mov_b32_e32 v66, v2
	v_mov_b32_e32 v67, v2
	v_mov_b32_e32 v68, v2
	v_mov_b32_e32 v69, v2
	v_mov_b32_e32 v70, v2
	v_mov_b32_e32 v71, v2
	v_mov_b32_e32 v72, v2
	v_mov_b32_e32 v73, v2
	v_mov_b32_e32 v100, v2
	v_mov_b32_e32 v101, v2
	v_mov_b32_e32 v102, v2
	v_mov_b32_e32 v103, v2
	v_mov_b32_e32 v104, v2
	v_mov_b32_e32 v105, v2
	v_mov_b32_e32 v106, v2
	v_mov_b32_e32 v107, v2
	v_mov_b32_e32 v116, v2
	v_mov_b32_e32 v117, v2
	v_mov_b32_e32 v118, v2
	v_mov_b32_e32 v119, v2
	v_mov_b32_e32 v120, v2
	v_mov_b32_e32 v121, v2
	v_mov_b32_e32 v122, v2
	v_mov_b32_e32 v123, v2
	v_mov_b32_e32 v132, v2
	v_mov_b32_e32 v133, v2
	v_mov_b32_e32 v134, v2
	v_mov_b32_e32 v135, v2
	v_mov_b32_e32 v136, v2
	v_mov_b32_e32 v137, v2
	v_mov_b32_e32 v138, v2
	v_mov_b32_e32 v139, v2
	v_mov_b32_e32 v74, v2
	v_mov_b32_e32 v75, v2
	v_mov_b32_e32 v76, v2
	v_mov_b32_e32 v77, v2
	v_mov_b32_e32 v78, v2
	v_mov_b32_e32 v79, v2
	v_mov_b32_e32 v80, v2
	v_mov_b32_e32 v81, v2
	v_mov_b32_e32 v108, v2
	v_mov_b32_e32 v109, v2
	v_mov_b32_e32 v110, v2
	v_mov_b32_e32 v111, v2
	v_mov_b32_e32 v112, v2
	v_mov_b32_e32 v113, v2
	v_mov_b32_e32 v114, v2
	v_mov_b32_e32 v115, v2
	v_mov_b32_e32 v124, v2
	v_mov_b32_e32 v125, v2
	v_mov_b32_e32 v126, v2
	v_mov_b32_e32 v127, v2
	v_mov_b32_e32 v128, v2
	v_mov_b32_e32 v129, v2
	v_mov_b32_e32 v130, v2
	v_mov_b32_e32 v131, v2
	v_mov_b32_e32 v140, v2
	v_mov_b32_e32 v141, v2
	v_mov_b32_e32 v142, v2
	v_mov_b32_e32 v143, v2
	v_mov_b32_e32 v144, v2
	v_mov_b32_e32 v145, v2
	v_mov_b32_e32 v146, v2
	v_mov_b32_e32 v147, v2
	s_nop 0
	s_nop 0
	s_nop 0
	s_nop 0
	s_nop 0
	s_nop 0

.LBB0_1528:
	s_add_u32 s33, s50, 0x100
	v_mov_b32_e32 v2, 0
	s_addc_u32 s56, s51, 0
	s_mov_b32 s57, -2
	v_mov_b32_e32 v3, v2
	v_mov_b32_e32 v4, v2
	v_mov_b32_e32 v5, v2
	v_mov_b32_e32 v6, v2
	v_mov_b32_e32 v7, v2
	v_mov_b32_e32 v8, v2
	v_mov_b32_e32 v9, v2
	v_mov_b32_e32 v10, v2
	v_mov_b32_e32 v11, v2
	v_mov_b32_e32 v12, v2
	v_mov_b32_e32 v13, v2
	v_mov_b32_e32 v14, v2
	v_mov_b32_e32 v15, v2
	v_mov_b32_e32 v16, v2
	v_mov_b32_e32 v17, v2
	v_mov_b32_e32 v18, v2
	v_mov_b32_e32 v19, v2
	v_mov_b32_e32 v20, v2
	v_mov_b32_e32 v21, v2
	v_mov_b32_e32 v22, v2
	v_mov_b32_e32 v23, v2
	v_mov_b32_e32 v24, v2
	v_mov_b32_e32 v25, v2
	v_mov_b32_e32 v26, v2
	v_mov_b32_e32 v27, v2
	v_mov_b32_e32 v28, v2
	v_mov_b32_e32 v29, v2
	v_mov_b32_e32 v30, v2
	v_mov_b32_e32 v31, v2
	v_mov_b32_e32 v32, v2
	v_mov_b32_e32 v33, v2
	v_mov_b32_e32 v66, v2
	v_mov_b32_e32 v67, v2
	v_mov_b32_e32 v68, v2
	v_mov_b32_e32 v69, v2
	v_mov_b32_e32 v70, v2
	v_mov_b32_e32 v71, v2
	v_mov_b32_e32 v72, v2
	v_mov_b32_e32 v73, v2
	v_mov_b32_e32 v74, v2
	v_mov_b32_e32 v75, v2
	v_mov_b32_e32 v76, v2
	v_mov_b32_e32 v77, v2
	v_mov_b32_e32 v78, v2
	v_mov_b32_e32 v79, v2
	v_mov_b32_e32 v80, v2
	v_mov_b32_e32 v81, v2
	v_mov_b32_e32 v82, v2
	v_mov_b32_e32 v83, v2
	v_mov_b32_e32 v84, v2
	v_mov_b32_e32 v85, v2
	v_mov_b32_e32 v86, v2
	v_mov_b32_e32 v87, v2
	v_mov_b32_e32 v88, v2
	v_mov_b32_e32 v89, v2
	v_mov_b32_e32 v90, v2
	v_mov_b32_e32 v91, v2
	v_mov_b32_e32 v92, v2
	v_mov_b32_e32 v93, v2
	v_mov_b32_e32 v94, v2
	v_mov_b32_e32 v95, v2
	v_mov_b32_e32 v96, v2
	v_mov_b32_e32 v97, v2
	v_mov_b32_e32 v34, v2
	v_mov_b32_e32 v35, v2
	v_mov_b32_e32 v36, v2
	v_mov_b32_e32 v37, v2
	v_mov_b32_e32 v38, v2
	v_mov_b32_e32 v39, v2
	v_mov_b32_e32 v40, v2
	v_mov_b32_e32 v41, v2
	v_mov_b32_e32 v42, v2
	v_mov_b32_e32 v43, v2
	v_mov_b32_e32 v44, v2
	v_mov_b32_e32 v45, v2
	v_mov_b32_e32 v46, v2
	v_mov_b32_e32 v47, v2
	v_mov_b32_e32 v48, v2
	v_mov_b32_e32 v49, v2
	v_mov_b32_e32 v50, v2
	v_mov_b32_e32 v51, v2
	v_mov_b32_e32 v52, v2
	v_mov_b32_e32 v53, v2
	v_mov_b32_e32 v54, v2
	v_mov_b32_e32 v55, v2
	v_mov_b32_e32 v56, v2
	v_mov_b32_e32 v57, v2
	v_mov_b32_e32 v58, v2
	v_mov_b32_e32 v59, v2
	v_mov_b32_e32 v60, v2
	v_mov_b32_e32 v61, v2
	v_mov_b32_e32 v62, v2
	v_mov_b32_e32 v63, v2
	v_mov_b32_e32 v64, v2
	v_mov_b32_e32 v65, v2
	v_mov_b32_e32 v100, v2
	v_mov_b32_e32 v101, v2
	v_mov_b32_e32 v102, v2
	v_mov_b32_e32 v103, v2
	v_mov_b32_e32 v104, v2
	v_mov_b32_e32 v105, v2
	v_mov_b32_e32 v106, v2
	v_mov_b32_e32 v107, v2
	v_mov_b32_e32 v108, v2
	v_mov_b32_e32 v109, v2
	v_mov_b32_e32 v110, v2
	v_mov_b32_e32 v111, v2
	v_mov_b32_e32 v112, v2
	v_mov_b32_e32 v113, v2
	v_mov_b32_e32 v114, v2
	v_mov_b32_e32 v115, v2
	v_mov_b32_e32 v116, v2
	v_mov_b32_e32 v117, v2
	v_mov_b32_e32 v118, v2
	v_mov_b32_e32 v119, v2
	v_mov_b32_e32 v120, v2
	v_mov_b32_e32 v121, v2
	v_mov_b32_e32 v122, v2
	v_mov_b32_e32 v123, v2
	v_mov_b32_e32 v124, v2
	v_mov_b32_e32 v125, v2
	v_mov_b32_e32 v126, v2
	v_mov_b32_e32 v127, v2
	v_mov_b32_e32 v128, v2
	v_mov_b32_e32 v129, v2
	v_mov_b32_e32 v130, v2
	v_mov_b32_e32 v131, v2
	s_nop 0
	s_nop 0
	s_nop 0
	s_nop 0
	s_nop 0
	s_nop 0
	s_nop 0
	s_nop 0
	s_nop 0
	s_nop 0
	s_nop 0
	s_nop 0
	s_nop 0
	s_nop 0
